# in-proj: 128 tiles split into 256 half tiles (row groups 4..7 of each wave skipped) so every CU pair gets 7.5 tile units instead of 8|7
# baseline (speedup 1.0000x reference)
.Lpj_entry:
	s_waitcnt lgkmcnt(0)
	s_load_dwordx2 s[48:49], s[0:1], 0xc0
	s_load_dwordx2 s[50:51], s[0:1], 0x98
	s_mov_b32 s59, 32
	s_mov_b32 s72, 0x100000
	s_mov_b32 s73, 0x3c000
	s_movk_i32 s32, 0x780
	s_getpc_b64 s[82:83]
	s_add_u32 s82, s82, ROPE_HI@rel32@lo+4
	s_addc_u32 s83, s83, ROPE_HI@rel32@hi+12
	s_getpc_b64 s[92:93]
	s_add_u32 s92, s92, ROPE_LO@rel32@lo+4
	s_addc_u32 s93, s93, ROPE_LO@rel32@hi+12
	s_mov_b32 s29, 0
	s_cmpk_eq_u32 s71, 0x200
	s_cbranch_scc0 .Lpj_noh
	s_mov_b32 s29, 1
	s_movk_i32 s32, 0x800
.Lpj_noh:
	v_and_b32_e32 v0, 63, v154
	v_lshrrev_b32_e32 v131, 6, v154
	v_lshrrev_b32_e32 v243, 2, v0
	v_readfirstlane_b32 s41, v131
	v_and_b32_e32 v130, 3, v0
	v_mov_b32_e32 v134, 0x1320
	s_nop 1
	s_lshr_b32 s42, s41, 1
	s_and_b32 s43, s41, 1
	v_bfe_u32 v132, v0, 4, 2
	v_lshlrev_b32_e32 v132, 2, v132
	v_lshrrev_b32_e32 v132, v132, v134
	v_and_b32_e32 v132, 3, v132
	v_xor_b32_e32 v132, v132, v130
	v_lshlrev_b32_e32 v245, 4, v132
	v_bfe_u32 v132, v0, 2, 2
	v_lshlrev_b32_e32 v132, 2, v132
	v_lshrrev_b32_e32 v132, v132, v134
	v_and_b32_e32 v132, 3, v132
	v_lshrrev_b32_e32 v133, 4, v0
	v_xor_b32_e32 v132, v132, v133
	v_lshlrev_b32_e32 v132, 4, v132
	v_and_b32_e32 v131, 15, v0
	s_lshl_b32 s26, s42, 13
	v_lshl_add_u32 v238, v131, 6, v132
	v_add_u32_e32 v238, s26, v238
	s_lshl_b32 s62, s41, 12
	s_lshl_b32 s63, s41, 11
	s_add_i32 s63, s63, 0x4000
	s_lshl_b32 s26, s43, 12
	s_add_i32 s26, s26, 0x4000
	v_lshrrev_b32_e32 v134, 2, v131
	v_lshl_add_u32 v239, v134, 9, v132
	v_and_b32_e32 v134, 3, v131
	v_lshl_add_u32 v239, v134, 6, v239
	v_add_u32_e32 v239, s26, v239
	v_mov_b32_e32 v134, 0x1320
	v_lshrrev_b32_e32 v246, 3, v243
	v_and_b32_e32 v246, 3, v246
	v_lshlrev_b32_e32 v246, 2, v246
	v_lshrrev_b32_e32 v246, v246, v134
	v_and_b32_e32 v246, 3, v246
	v_xor_b32_e32 v246, v246, v130
	v_lshlrev_b32_e32 v246, 4, v246
	v_lshrrev_b32_e32 v247, 3, v243
	v_add_u32_e32 v247, 2, v247
	v_and_b32_e32 v247, 3, v247
	v_lshlrev_b32_e32 v247, 2, v247
	v_lshrrev_b32_e32 v247, v247, v134
	v_and_b32_e32 v247, 3, v247
	v_xor_b32_e32 v247, v247, v130
	v_lshlrev_b32_e32 v247, 4, v247
	s_lshl_b32 s26, s42, 7
	v_add_u32_e32 v227, s26, v131
	v_lshlrev_b32_e32 v228, 4, v133
	s_mov_b32 s34, s3
	s_cmp_lt_i32 s34, s32
	s_cbranch_scc0 .Lpj_done
	s_mov_b32 s24, 0
	s_mov_b32 s20, s34
	s_cmp_eq_u32 s29, 0
	s_cbranch_scc1 .Lpj_hc_f
	s_cmpk_lt_u32 s34, 0x700
	s_cbranch_scc1 .Lpj_hc_f
	s_add_i32 s20, s34, 0xfffff900
	s_and_b32 s24, s20, 1
	s_add_i32 s24, s24, 1
	s_lshr_b32 s20, s20, 1
	s_add_i32 s20, s20, 0x700
.Lpj_hc_f:
	s_and_b32 s26, s20, 7
	s_lshr_b32 s27, s20, 3
	s_lshr_b32 s36, s27, 3
	s_and_b32 s27, s27, 7
	s_lshl_b32 s27, s27, 3
	s_add_i32 s35, s27, s26
	s_lshl_b32 s35, s35, 8
	s_lshl_b32 s36, s36, 7
	s_lshr_b32 s26, s24, 1
	s_lshl_b32 s26, s26, 6
	s_add_i32 s35, s35, s26
	s_lshl_b32 s26, s41, 6
	s_add_i32 s26, s26, s35
	v_add_u32_e32 v0, s26, v243
	v_lshl_add_u32 v226, v0, 6, v245
	s_lshl_b32 s26, s41, 5
	s_add_i32 s26, s26, s36
	v_add_u32_e32 v0, s26, v243
	v_lshl_add_u32 v230, v0, 6, v246
	v_lshl_add_u32 v231, v0, 6, v247
	s_mov_b32 s60, 0
	s_mov_b32 s61, 0
	s_waitcnt lgkmcnt(0)
	s_mov_b64 s[54:55], s[48:49]
	s_mov_b64 s[56:57], s[50:51]
	s_add_i32 m0, s60, s62
	s_nop 0
	global_load_lds_dwordx4 v226, s[54:55]
	global_load_lds_dwordx4 v226, s[54:55] offset:1024
	global_load_lds_dwordx4 v226, s[54:55] offset:2048
	global_load_lds_dwordx4 v226, s[54:55] offset:3072
	s_add_i32 m0, s60, s63
	s_nop 0
	global_load_lds_dwordx4 v230, s[56:57]
	global_load_lds_dwordx4 v231, s[56:57] offset:1024
	s_add_i32 s60, s60, 0x6000
	s_cmp_eq_u32 s60, 0x12000
	s_cselect_b32 s60, 0, s60
	s_add_u32 s54, s54, s72
	s_addc_u32 s55, s55, 0
	s_add_u32 s56, s56, s73
	s_addc_u32 s57, s57, 0
	s_add_i32 m0, s60, s62
	s_nop 0
	global_load_lds_dwordx4 v226, s[54:55]
	global_load_lds_dwordx4 v226, s[54:55] offset:1024
	global_load_lds_dwordx4 v226, s[54:55] offset:2048
	global_load_lds_dwordx4 v226, s[54:55] offset:3072
	s_add_i32 m0, s60, s63
	s_nop 0
	global_load_lds_dwordx4 v230, s[56:57]
	global_load_lds_dwordx4 v231, s[56:57] offset:1024
	s_add_i32 s60, s60, 0x6000
	s_cmp_eq_u32 s60, 0x12000
	s_cselect_b32 s60, 0, s60
	s_add_u32 s54, s54, s72
	s_addc_u32 s55, s55, 0
	s_add_u32 s56, s56, s73
	s_addc_u32 s57, s57, 0
	s_add_i32 m0, s60, s62
	s_nop 0
	global_load_lds_dwordx4 v226, s[54:55]
	global_load_lds_dwordx4 v226, s[54:55] offset:1024
	global_load_lds_dwordx4 v226, s[54:55] offset:2048
	global_load_lds_dwordx4 v226, s[54:55] offset:3072
	s_add_i32 m0, s60, s63
	s_nop 0
	global_load_lds_dwordx4 v230, s[56:57]
	global_load_lds_dwordx4 v231, s[56:57] offset:1024
	s_add_i32 s60, s60, 0x6000
	s_cmp_eq_u32 s60, 0x12000
	s_cselect_b32 s60, 0, s60
	s_add_u32 s54, s54, s72
	s_addc_u32 s55, s55, 0
	s_add_u32 s56, s56, s73
	s_addc_u32 s57, s57, 0
	s_waitcnt vmcnt(12)
	s_barrier
	v_add_u32_e32 v240, s61, v238
	v_add_u32_e32 v241, s61, v239
	ds_read_b128 v[162:165], v241 offset:0
	ds_read_b128 v[166:169], v241 offset:256
	ds_read_b128 v[170:173], v241 offset:2048
	ds_read_b128 v[174:177], v241 offset:2304
	ds_read_b128 v[130:133], v240 offset:0
	ds_read_b128 v[134:137], v240 offset:1024
	ds_read_b128 v[138:141], v240 offset:2048
	ds_read_b128 v[142:145], v240 offset:3072
	ds_read_b128 v[146:149], v240 offset:4096
	ds_read_b128 v[150:153], v240 offset:5120
	ds_read_b128 v[154:157], v240 offset:6144
	ds_read_b128 v[158:161], v240 offset:7168
	s_add_i32 s61, s61, 0x6000
	s_cmp_eq_u32 s61, 0x12000
	s_cselect_b32 s61, 0, s61
	s_add_i32 s38, s34, s71
	s_cmp_lt_i32 s38, s32
	s_cselect_b32 s37, 1, 0
	s_cbranch_scc0 .Lpj_nn_a
	s_mov_b32 s28, 0
	s_mov_b32 s20, s38
	s_cmp_eq_u32 s29, 0
	s_cbranch_scc1 .Lpj_hc_a
	s_cmpk_lt_u32 s38, 0x700
	s_cbranch_scc1 .Lpj_hc_a
	s_add_i32 s20, s38, 0xfffff900
	s_and_b32 s28, s20, 1
	s_add_i32 s28, s28, 1
	s_lshr_b32 s20, s20, 1
	s_add_i32 s20, s20, 0x700
.Lpj_hc_a:
	s_and_b32 s26, s20, 7
	s_lshr_b32 s27, s20, 3
	s_lshr_b32 s31, s27, 3
	s_and_b32 s27, s27, 7
	s_lshl_b32 s27, s27, 3
	s_add_i32 s30, s27, s26
	s_lshl_b32 s30, s30, 8
	s_lshl_b32 s31, s31, 7
	s_lshr_b32 s26, s28, 1
	s_lshl_b32 s26, s26, 6
	s_add_i32 s30, s30, s26
	s_lshl_b32 s26, s41, 6
	s_add_i32 s26, s26, s30
	v_add_u32_e32 v0, s26, v243
	v_lshl_add_u32 v232, v0, 6, v245
	s_lshl_b32 s26, s41, 5
	s_add_i32 s26, s26, s31
	v_add_u32_e32 v0, s26, v243
	v_lshl_add_u32 v236, v0, 6, v246
	v_lshl_add_u32 v237, v0, 6, v247
.Lpj_nn_a:
	s_waitcnt vmcnt(6) lgkmcnt(0)
	s_barrier
	v_add_u32_e32 v240, s61, v238
	v_add_u32_e32 v241, s61, v239
	s_add_i32 m0, s60, s62
	v_mfma_f32_16x16x32_bf16 v[2:5], v[162:165], v[130:133], 0
	global_load_lds_dwordx4 v226, s[54:55]
	v_mfma_f32_16x16x32_bf16 v[6:9], v[166:169], v[130:133], 0
	global_load_lds_dwordx4 v226, s[54:55] offset:1024
	v_mfma_f32_16x16x32_bf16 v[10:13], v[170:173], v[130:133], 0
	global_load_lds_dwordx4 v226, s[54:55] offset:2048
	v_mfma_f32_16x16x32_bf16 v[14:17], v[174:177], v[130:133], 0
	global_load_lds_dwordx4 v226, s[54:55] offset:3072
	s_add_i32 m0, s60, s63
	v_mfma_f32_16x16x32_bf16 v[18:21], v[162:165], v[134:137], 0
	global_load_lds_dwordx4 v230, s[56:57]
	v_mfma_f32_16x16x32_bf16 v[22:25], v[166:169], v[134:137], 0
	global_load_lds_dwordx4 v231, s[56:57] offset:1024
	v_mfma_f32_16x16x32_bf16 v[26:29], v[170:173], v[134:137], 0
	v_mfma_f32_16x16x32_bf16 v[30:33], v[174:177], v[134:137], 0
	v_mfma_f32_16x16x32_bf16 v[34:37], v[162:165], v[138:141], 0
	ds_read_b128 v[210:213], v241 offset:0
	v_mfma_f32_16x16x32_bf16 v[38:41], v[166:169], v[138:141], 0
	ds_read_b128 v[214:217], v241 offset:256
	v_mfma_f32_16x16x32_bf16 v[42:45], v[170:173], v[138:141], 0
	ds_read_b128 v[218:221], v241 offset:2048
	v_mfma_f32_16x16x32_bf16 v[46:49], v[174:177], v[138:141], 0
	ds_read_b128 v[222:225], v241 offset:2304
	v_mfma_f32_16x16x32_bf16 v[50:53], v[162:165], v[142:145], 0
	ds_read_b128 v[178:181], v240 offset:0
	v_mfma_f32_16x16x32_bf16 v[54:57], v[166:169], v[142:145], 0
	ds_read_b128 v[182:185], v240 offset:1024
	v_mfma_f32_16x16x32_bf16 v[58:61], v[170:173], v[142:145], 0
	ds_read_b128 v[186:189], v240 offset:2048
	v_mfma_f32_16x16x32_bf16 v[62:65], v[174:177], v[142:145], 0
	ds_read_b128 v[190:193], v240 offset:3072
	s_cmp_lg_u32 s24, 0
	s_cbranch_scc1 .Lpj_hs1
	v_mfma_f32_16x16x32_bf16 v[66:69], v[162:165], v[146:149], 0
	ds_read_b128 v[194:197], v240 offset:4096
	v_mfma_f32_16x16x32_bf16 v[70:73], v[166:169], v[146:149], 0
	ds_read_b128 v[198:201], v240 offset:5120
	v_mfma_f32_16x16x32_bf16 v[74:77], v[170:173], v[146:149], 0
	ds_read_b128 v[202:205], v240 offset:6144
	v_mfma_f32_16x16x32_bf16 v[78:81], v[174:177], v[146:149], 0
	ds_read_b128 v[206:209], v240 offset:7168
	s_setprio 1
	v_mfma_f32_16x16x32_bf16 v[82:85], v[162:165], v[150:153], 0
	v_mfma_f32_16x16x32_bf16 v[86:89], v[166:169], v[150:153], 0
	v_mfma_f32_16x16x32_bf16 v[90:93], v[170:173], v[150:153], 0
	v_mfma_f32_16x16x32_bf16 v[94:97], v[174:177], v[150:153], 0
	v_mfma_f32_16x16x32_bf16 v[98:101], v[162:165], v[154:157], 0
	v_mfma_f32_16x16x32_bf16 v[102:105], v[166:169], v[154:157], 0
	v_mfma_f32_16x16x32_bf16 v[106:109], v[170:173], v[154:157], 0
	v_mfma_f32_16x16x32_bf16 v[110:113], v[174:177], v[154:157], 0
	v_mfma_f32_16x16x32_bf16 v[114:117], v[162:165], v[158:161], 0
	v_mfma_f32_16x16x32_bf16 v[118:121], v[166:169], v[158:161], 0
	v_mfma_f32_16x16x32_bf16 v[122:125], v[170:173], v[158:161], 0
	v_mfma_f32_16x16x32_bf16 v[126:129], v[174:177], v[158:161], 0
.Lpj_hs1:
	s_setprio 0
	s_add_i32 s60, s60, 0x6000
	s_cmp_eq_u32 s60, 0x12000
	s_cselect_b32 s60, 0, s60
	s_add_u32 s54, s54, s72
	s_addc_u32 s55, s55, 0
	s_add_u32 s56, s56, s73
	s_addc_u32 s57, s57, 0
	s_add_i32 s61, s61, 0x6000
	s_cmp_eq_u32 s61, 0x12000
	s_cselect_b32 s61, 0, s61
	s_waitcnt vmcnt(6) lgkmcnt(0)
	s_barrier
	v_add_u32_e32 v240, s61, v238
	v_add_u32_e32 v241, s61, v239
	s_add_i32 m0, s60, s62
	v_mfma_f32_16x16x32_bf16 v[2:5], v[210:213], v[178:181], v[2:5]
	global_load_lds_dwordx4 v226, s[54:55]
	v_mfma_f32_16x16x32_bf16 v[6:9], v[214:217], v[178:181], v[6:9]
	global_load_lds_dwordx4 v226, s[54:55] offset:1024
	v_mfma_f32_16x16x32_bf16 v[10:13], v[218:221], v[178:181], v[10:13]
	global_load_lds_dwordx4 v226, s[54:55] offset:2048
	v_mfma_f32_16x16x32_bf16 v[14:17], v[222:225], v[178:181], v[14:17]
	global_load_lds_dwordx4 v226, s[54:55] offset:3072
	s_add_i32 m0, s60, s63
	v_mfma_f32_16x16x32_bf16 v[18:21], v[210:213], v[182:185], v[18:21]
	global_load_lds_dwordx4 v230, s[56:57]
	v_mfma_f32_16x16x32_bf16 v[22:25], v[214:217], v[182:185], v[22:25]
	global_load_lds_dwordx4 v231, s[56:57] offset:1024
	v_mfma_f32_16x16x32_bf16 v[26:29], v[218:221], v[182:185], v[26:29]
	v_mfma_f32_16x16x32_bf16 v[30:33], v[222:225], v[182:185], v[30:33]
	v_mfma_f32_16x16x32_bf16 v[34:37], v[210:213], v[186:189], v[34:37]
	ds_read_b128 v[162:165], v241 offset:0
	v_mfma_f32_16x16x32_bf16 v[38:41], v[214:217], v[186:189], v[38:41]
	ds_read_b128 v[166:169], v241 offset:256
	v_mfma_f32_16x16x32_bf16 v[42:45], v[218:221], v[186:189], v[42:45]
	ds_read_b128 v[170:173], v241 offset:2048
	v_mfma_f32_16x16x32_bf16 v[46:49], v[222:225], v[186:189], v[46:49]
	ds_read_b128 v[174:177], v241 offset:2304
	v_mfma_f32_16x16x32_bf16 v[50:53], v[210:213], v[190:193], v[50:53]
	ds_read_b128 v[130:133], v240 offset:0
	v_mfma_f32_16x16x32_bf16 v[54:57], v[214:217], v[190:193], v[54:57]
	ds_read_b128 v[134:137], v240 offset:1024
	v_mfma_f32_16x16x32_bf16 v[58:61], v[218:221], v[190:193], v[58:61]
	ds_read_b128 v[138:141], v240 offset:2048
	v_mfma_f32_16x16x32_bf16 v[62:65], v[222:225], v[190:193], v[62:65]
	ds_read_b128 v[142:145], v240 offset:3072
	s_cmp_lg_u32 s24, 0
	s_cbranch_scc1 .Lpj_hs2
	v_mfma_f32_16x16x32_bf16 v[66:69], v[210:213], v[194:197], v[66:69]
	ds_read_b128 v[146:149], v240 offset:4096
	v_mfma_f32_16x16x32_bf16 v[70:73], v[214:217], v[194:197], v[70:73]
	ds_read_b128 v[150:153], v240 offset:5120
	v_mfma_f32_16x16x32_bf16 v[74:77], v[218:221], v[194:197], v[74:77]
	ds_read_b128 v[154:157], v240 offset:6144
	v_mfma_f32_16x16x32_bf16 v[78:81], v[222:225], v[194:197], v[78:81]
	ds_read_b128 v[158:161], v240 offset:7168
	s_setprio 1
	v_mfma_f32_16x16x32_bf16 v[82:85], v[210:213], v[198:201], v[82:85]
	v_mfma_f32_16x16x32_bf16 v[86:89], v[214:217], v[198:201], v[86:89]
	v_mfma_f32_16x16x32_bf16 v[90:93], v[218:221], v[198:201], v[90:93]
	v_mfma_f32_16x16x32_bf16 v[94:97], v[222:225], v[198:201], v[94:97]
	v_mfma_f32_16x16x32_bf16 v[98:101], v[210:213], v[202:205], v[98:101]
	v_mfma_f32_16x16x32_bf16 v[102:105], v[214:217], v[202:205], v[102:105]
	v_mfma_f32_16x16x32_bf16 v[106:109], v[218:221], v[202:205], v[106:109]
	v_mfma_f32_16x16x32_bf16 v[110:113], v[222:225], v[202:205], v[110:113]
	v_mfma_f32_16x16x32_bf16 v[114:117], v[210:213], v[206:209], v[114:117]
	v_mfma_f32_16x16x32_bf16 v[118:121], v[214:217], v[206:209], v[118:121]
	v_mfma_f32_16x16x32_bf16 v[122:125], v[218:221], v[206:209], v[122:125]
	v_mfma_f32_16x16x32_bf16 v[126:129], v[222:225], v[206:209], v[126:129]
.Lpj_hs2:
	s_setprio 0
	s_add_i32 s60, s60, 0x6000
	s_cmp_eq_u32 s60, 0x12000
	s_cselect_b32 s60, 0, s60
	s_add_u32 s54, s54, s72
	s_addc_u32 s55, s55, 0
	s_add_u32 s56, s56, s73
	s_addc_u32 s57, s57, 0
	s_add_i32 s61, s61, 0x6000
	s_cmp_eq_u32 s61, 0x12000
	s_cselect_b32 s61, 0, s61
	s_branch .Lpj_main
.Lpj_tile:
	s_add_i32 s38, s34, s71
	s_cmp_lt_i32 s38, s32
	s_cselect_b32 s37, 1, 0
	s_cbranch_scc0 .Lpj_nn_b
	s_mov_b32 s28, 0
	s_mov_b32 s20, s38
	s_cmp_eq_u32 s29, 0
	s_cbranch_scc1 .Lpj_hc_b
	s_cmpk_lt_u32 s38, 0x700
	s_cbranch_scc1 .Lpj_hc_b
	s_add_i32 s20, s38, 0xfffff900
	s_and_b32 s28, s20, 1
	s_add_i32 s28, s28, 1
	s_lshr_b32 s20, s20, 1
	s_add_i32 s20, s20, 0x700

.Lpj_nn_b:
	s_waitcnt vmcnt(63) lgkmcnt(0)
	s_barrier
	v_add_u32_e32 v240, s61, v238
	v_add_u32_e32 v241, s61, v239
	s_add_i32 m0, s60, s62
	v_mfma_f32_16x16x32_bf16 v[2:5], v[162:165], v[130:133], 0
	global_load_lds_dwordx4 v226, s[54:55]
	v_mfma_f32_16x16x32_bf16 v[6:9], v[166:169], v[130:133], 0
	global_load_lds_dwordx4 v226, s[54:55] offset:1024
	v_mfma_f32_16x16x32_bf16 v[10:13], v[170:173], v[130:133], 0
	global_load_lds_dwordx4 v226, s[54:55] offset:2048
	v_mfma_f32_16x16x32_bf16 v[14:17], v[174:177], v[130:133], 0
	global_load_lds_dwordx4 v226, s[54:55] offset:3072
	s_add_i32 m0, s60, s63
	v_mfma_f32_16x16x32_bf16 v[18:21], v[162:165], v[134:137], 0
	global_load_lds_dwordx4 v230, s[56:57]
	v_mfma_f32_16x16x32_bf16 v[22:25], v[166:169], v[134:137], 0
	global_load_lds_dwordx4 v231, s[56:57] offset:1024
	v_mfma_f32_16x16x32_bf16 v[26:29], v[170:173], v[134:137], 0
	v_mfma_f32_16x16x32_bf16 v[30:33], v[174:177], v[134:137], 0
	v_mfma_f32_16x16x32_bf16 v[34:37], v[162:165], v[138:141], 0
	ds_read_b128 v[210:213], v241 offset:0
	v_mfma_f32_16x16x32_bf16 v[38:41], v[166:169], v[138:141], 0
	ds_read_b128 v[214:217], v241 offset:256
	v_mfma_f32_16x16x32_bf16 v[42:45], v[170:173], v[138:141], 0
	ds_read_b128 v[218:221], v241 offset:2048
	v_mfma_f32_16x16x32_bf16 v[46:49], v[174:177], v[138:141], 0
	ds_read_b128 v[222:225], v241 offset:2304
	v_mfma_f32_16x16x32_bf16 v[50:53], v[162:165], v[142:145], 0
	ds_read_b128 v[178:181], v240 offset:0
	v_mfma_f32_16x16x32_bf16 v[54:57], v[166:169], v[142:145], 0
	ds_read_b128 v[182:185], v240 offset:1024
	v_mfma_f32_16x16x32_bf16 v[58:61], v[170:173], v[142:145], 0
	ds_read_b128 v[186:189], v240 offset:2048
	v_mfma_f32_16x16x32_bf16 v[62:65], v[174:177], v[142:145], 0
	ds_read_b128 v[190:193], v240 offset:3072
	s_cmp_lg_u32 s24, 0
	s_cbranch_scc1 .Lpj_hs3
	v_mfma_f32_16x16x32_bf16 v[66:69], v[162:165], v[146:149], 0
	ds_read_b128 v[194:197], v240 offset:4096
	v_mfma_f32_16x16x32_bf16 v[70:73], v[166:169], v[146:149], 0
	ds_read_b128 v[198:201], v240 offset:5120
	v_mfma_f32_16x16x32_bf16 v[74:77], v[170:173], v[146:149], 0
	ds_read_b128 v[202:205], v240 offset:6144
	v_mfma_f32_16x16x32_bf16 v[78:81], v[174:177], v[146:149], 0
	ds_read_b128 v[206:209], v240 offset:7168
	s_setprio 1
	v_mfma_f32_16x16x32_bf16 v[82:85], v[162:165], v[150:153], 0
	v_mfma_f32_16x16x32_bf16 v[86:89], v[166:169], v[150:153], 0
	v_mfma_f32_16x16x32_bf16 v[90:93], v[170:173], v[150:153], 0
	v_mfma_f32_16x16x32_bf16 v[94:97], v[174:177], v[150:153], 0
	v_mfma_f32_16x16x32_bf16 v[98:101], v[162:165], v[154:157], 0
	v_mfma_f32_16x16x32_bf16 v[102:105], v[166:169], v[154:157], 0
	v_mfma_f32_16x16x32_bf16 v[106:109], v[170:173], v[154:157], 0
	v_mfma_f32_16x16x32_bf16 v[110:113], v[174:177], v[154:157], 0
	v_mfma_f32_16x16x32_bf16 v[114:117], v[162:165], v[158:161], 0
	v_mfma_f32_16x16x32_bf16 v[118:121], v[166:169], v[158:161], 0
	v_mfma_f32_16x16x32_bf16 v[122:125], v[170:173], v[158:161], 0
	v_mfma_f32_16x16x32_bf16 v[126:129], v[174:177], v[158:161], 0
.Lpj_hs3:
	s_setprio 0
	s_add_i32 s60, s60, 0x6000
	s_cmp_eq_u32 s60, 0x12000
	s_cselect_b32 s60, 0, s60
	s_add_u32 s54, s54, s72
	s_addc_u32 s55, s55, 0
	s_add_u32 s56, s56, s73
	s_addc_u32 s57, s57, 0
	s_add_i32 s61, s61, 0x6000
	s_cmp_eq_u32 s61, 0x12000
	s_cselect_b32 s61, 0, s61
	s_waitcnt vmcnt(63) lgkmcnt(0)
	s_barrier
	v_add_u32_e32 v240, s61, v238
	v_add_u32_e32 v241, s61, v239
	s_add_i32 m0, s60, s62
	v_mfma_f32_16x16x32_bf16 v[2:5], v[210:213], v[178:181], v[2:5]
	global_load_lds_dwordx4 v226, s[54:55]
	v_mfma_f32_16x16x32_bf16 v[6:9], v[214:217], v[178:181], v[6:9]
	global_load_lds_dwordx4 v226, s[54:55] offset:1024
	v_mfma_f32_16x16x32_bf16 v[10:13], v[218:221], v[178:181], v[10:13]
	global_load_lds_dwordx4 v226, s[54:55] offset:2048
	v_mfma_f32_16x16x32_bf16 v[14:17], v[222:225], v[178:181], v[14:17]
	global_load_lds_dwordx4 v226, s[54:55] offset:3072
	s_add_i32 m0, s60, s63
	v_mfma_f32_16x16x32_bf16 v[18:21], v[210:213], v[182:185], v[18:21]
	global_load_lds_dwordx4 v230, s[56:57]
	v_mfma_f32_16x16x32_bf16 v[22:25], v[214:217], v[182:185], v[22:25]
	global_load_lds_dwordx4 v231, s[56:57] offset:1024
	v_mfma_f32_16x16x32_bf16 v[26:29], v[218:221], v[182:185], v[26:29]
	v_mfma_f32_16x16x32_bf16 v[30:33], v[222:225], v[182:185], v[30:33]
	v_mfma_f32_16x16x32_bf16 v[34:37], v[210:213], v[186:189], v[34:37]
	ds_read_b128 v[162:165], v241 offset:0
	v_mfma_f32_16x16x32_bf16 v[38:41], v[214:217], v[186:189], v[38:41]
	ds_read_b128 v[166:169], v241 offset:256
	v_mfma_f32_16x16x32_bf16 v[42:45], v[218:221], v[186:189], v[42:45]
	ds_read_b128 v[170:173], v241 offset:2048
	v_mfma_f32_16x16x32_bf16 v[46:49], v[222:225], v[186:189], v[46:49]
	ds_read_b128 v[174:177], v241 offset:2304
	v_mfma_f32_16x16x32_bf16 v[50:53], v[210:213], v[190:193], v[50:53]
	ds_read_b128 v[130:133], v240 offset:0
	v_mfma_f32_16x16x32_bf16 v[54:57], v[214:217], v[190:193], v[54:57]
	ds_read_b128 v[134:137], v240 offset:1024
	v_mfma_f32_16x16x32_bf16 v[58:61], v[218:221], v[190:193], v[58:61]
	ds_read_b128 v[138:141], v240 offset:2048
	v_mfma_f32_16x16x32_bf16 v[62:65], v[222:225], v[190:193], v[62:65]
	ds_read_b128 v[142:145], v240 offset:3072
	s_cmp_lg_u32 s24, 0
	s_cbranch_scc1 .Lpj_hs4
	v_mfma_f32_16x16x32_bf16 v[66:69], v[210:213], v[194:197], v[66:69]
	ds_read_b128 v[146:149], v240 offset:4096
	v_mfma_f32_16x16x32_bf16 v[70:73], v[214:217], v[194:197], v[70:73]
	ds_read_b128 v[150:153], v240 offset:5120
	v_mfma_f32_16x16x32_bf16 v[74:77], v[218:221], v[194:197], v[74:77]
	ds_read_b128 v[154:157], v240 offset:6144
	v_mfma_f32_16x16x32_bf16 v[78:81], v[222:225], v[194:197], v[78:81]
	ds_read_b128 v[158:161], v240 offset:7168
	s_setprio 1
	v_mfma_f32_16x16x32_bf16 v[82:85], v[210:213], v[198:201], v[82:85]
	v_mfma_f32_16x16x32_bf16 v[86:89], v[214:217], v[198:201], v[86:89]
	v_mfma_f32_16x16x32_bf16 v[90:93], v[218:221], v[198:201], v[90:93]
	v_mfma_f32_16x16x32_bf16 v[94:97], v[222:225], v[198:201], v[94:97]
	v_mfma_f32_16x16x32_bf16 v[98:101], v[210:213], v[202:205], v[98:101]
	v_mfma_f32_16x16x32_bf16 v[102:105], v[214:217], v[202:205], v[102:105]
	v_mfma_f32_16x16x32_bf16 v[106:109], v[218:221], v[202:205], v[106:109]
	v_mfma_f32_16x16x32_bf16 v[110:113], v[222:225], v[202:205], v[110:113]
	v_mfma_f32_16x16x32_bf16 v[114:117], v[210:213], v[206:209], v[114:117]
	v_mfma_f32_16x16x32_bf16 v[118:121], v[214:217], v[206:209], v[118:121]
	v_mfma_f32_16x16x32_bf16 v[122:125], v[218:221], v[206:209], v[122:125]
	v_mfma_f32_16x16x32_bf16 v[126:129], v[222:225], v[206:209], v[126:129]
.Lpj_hs4:
	s_setprio 0
	s_add_i32 s60, s60, 0x6000
	s_cmp_eq_u32 s60, 0x12000
	s_cselect_b32 s60, 0, s60
	s_add_u32 s54, s54, s72
	s_addc_u32 s55, s55, 0
	s_add_u32 s56, s56, s73
	s_addc_u32 s57, s57, 0
	s_add_i32 s61, s61, 0x6000
	s_cmp_eq_u32 s61, 0x12000
	s_cselect_b32 s61, 0, s61

.Lpj_kloop:
	s_waitcnt vmcnt(6) lgkmcnt(0)
	s_barrier
	v_add_u32_e32 v240, s61, v238
	v_add_u32_e32 v241, s61, v239
	s_add_i32 m0, s60, s62
	v_mfma_f32_16x16x32_bf16 v[2:5], v[162:165], v[130:133], v[2:5]
	global_load_lds_dwordx4 v226, s[54:55]
	v_mfma_f32_16x16x32_bf16 v[6:9], v[166:169], v[130:133], v[6:9]
	global_load_lds_dwordx4 v226, s[54:55] offset:1024
	v_mfma_f32_16x16x32_bf16 v[10:13], v[170:173], v[130:133], v[10:13]
	global_load_lds_dwordx4 v226, s[54:55] offset:2048
	v_mfma_f32_16x16x32_bf16 v[14:17], v[174:177], v[130:133], v[14:17]
	global_load_lds_dwordx4 v226, s[54:55] offset:3072
	s_add_i32 m0, s60, s63
	v_mfma_f32_16x16x32_bf16 v[18:21], v[162:165], v[134:137], v[18:21]
	global_load_lds_dwordx4 v230, s[56:57]
	v_mfma_f32_16x16x32_bf16 v[22:25], v[166:169], v[134:137], v[22:25]
	global_load_lds_dwordx4 v231, s[56:57] offset:1024
	v_mfma_f32_16x16x32_bf16 v[26:29], v[170:173], v[134:137], v[26:29]
	v_mfma_f32_16x16x32_bf16 v[30:33], v[174:177], v[134:137], v[30:33]
	v_mfma_f32_16x16x32_bf16 v[34:37], v[162:165], v[138:141], v[34:37]
	ds_read_b128 v[210:213], v241 offset:0
	v_mfma_f32_16x16x32_bf16 v[38:41], v[166:169], v[138:141], v[38:41]
	ds_read_b128 v[214:217], v241 offset:256
	v_mfma_f32_16x16x32_bf16 v[42:45], v[170:173], v[138:141], v[42:45]
	ds_read_b128 v[218:221], v241 offset:2048
	v_mfma_f32_16x16x32_bf16 v[46:49], v[174:177], v[138:141], v[46:49]
	ds_read_b128 v[222:225], v241 offset:2304
	v_mfma_f32_16x16x32_bf16 v[50:53], v[162:165], v[142:145], v[50:53]
	ds_read_b128 v[178:181], v240 offset:0
	v_mfma_f32_16x16x32_bf16 v[54:57], v[166:169], v[142:145], v[54:57]
	ds_read_b128 v[182:185], v240 offset:1024
	v_mfma_f32_16x16x32_bf16 v[58:61], v[170:173], v[142:145], v[58:61]
	ds_read_b128 v[186:189], v240 offset:2048
	v_mfma_f32_16x16x32_bf16 v[62:65], v[174:177], v[142:145], v[62:65]
	ds_read_b128 v[190:193], v240 offset:3072
	s_cmp_lg_u32 s24, 0
	s_cbranch_scc1 .Lpj_hs5
	v_mfma_f32_16x16x32_bf16 v[66:69], v[162:165], v[146:149], v[66:69]
	ds_read_b128 v[194:197], v240 offset:4096
	v_mfma_f32_16x16x32_bf16 v[70:73], v[166:169], v[146:149], v[70:73]
	ds_read_b128 v[198:201], v240 offset:5120
	v_mfma_f32_16x16x32_bf16 v[74:77], v[170:173], v[146:149], v[74:77]
	ds_read_b128 v[202:205], v240 offset:6144
	v_mfma_f32_16x16x32_bf16 v[78:81], v[174:177], v[146:149], v[78:81]
	ds_read_b128 v[206:209], v240 offset:7168
	s_setprio 1
	v_mfma_f32_16x16x32_bf16 v[82:85], v[162:165], v[150:153], v[82:85]
	v_mfma_f32_16x16x32_bf16 v[86:89], v[166:169], v[150:153], v[86:89]
	v_mfma_f32_16x16x32_bf16 v[90:93], v[170:173], v[150:153], v[90:93]
	v_mfma_f32_16x16x32_bf16 v[94:97], v[174:177], v[150:153], v[94:97]
	v_mfma_f32_16x16x32_bf16 v[98:101], v[162:165], v[154:157], v[98:101]
	v_mfma_f32_16x16x32_bf16 v[102:105], v[166:169], v[154:157], v[102:105]
	v_mfma_f32_16x16x32_bf16 v[106:109], v[170:173], v[154:157], v[106:109]
	v_mfma_f32_16x16x32_bf16 v[110:113], v[174:177], v[154:157], v[110:113]
	v_mfma_f32_16x16x32_bf16 v[114:117], v[162:165], v[158:161], v[114:117]
	v_mfma_f32_16x16x32_bf16 v[118:121], v[166:169], v[158:161], v[118:121]
	v_mfma_f32_16x16x32_bf16 v[122:125], v[170:173], v[158:161], v[122:125]
	v_mfma_f32_16x16x32_bf16 v[126:129], v[174:177], v[158:161], v[126:129]

.Lpj_hs6:
	s_setprio 0
	s_add_i32 s60, s60, 0x6000
	s_cmp_eq_u32 s60, 0x12000
	s_cselect_b32 s60, 0, s60
	s_add_u32 s54, s54, s72
	s_addc_u32 s55, s55, 0
	s_add_u32 s56, s56, s73
	s_addc_u32 s57, s57, 0
	s_add_i32 s61, s61, 0x6000
	s_cmp_eq_u32 s61, 0x12000
	s_cselect_b32 s61, 0, s61
	s_add_i32 s40, s40, -1
	s_cmp_lg_u32 s40, 0
	s_cbranch_scc1 .Lpj_kloop
.Lpj_kdone:
	s_cmp_eq_u32 s37, 0
	s_cbranch_scc1 .Lpj_tail_last
	s_waitcnt vmcnt(6) lgkmcnt(0)
	s_barrier
	v_add_u32_e32 v240, s61, v238
	v_add_u32_e32 v241, s61, v239
	s_add_i32 m0, s60, s62
	v_mfma_f32_16x16x32_bf16 v[2:5], v[162:165], v[130:133], v[2:5]
	global_load_lds_dwordx4 v226, s[54:55]
	v_mfma_f32_16x16x32_bf16 v[6:9], v[166:169], v[130:133], v[6:9]
	global_load_lds_dwordx4 v226, s[54:55] offset:1024
	v_mfma_f32_16x16x32_bf16 v[10:13], v[170:173], v[130:133], v[10:13]
	global_load_lds_dwordx4 v226, s[54:55] offset:2048
	v_mfma_f32_16x16x32_bf16 v[14:17], v[174:177], v[130:133], v[14:17]
	global_load_lds_dwordx4 v226, s[54:55] offset:3072
	s_add_i32 m0, s60, s63
	v_mfma_f32_16x16x32_bf16 v[18:21], v[162:165], v[134:137], v[18:21]
	global_load_lds_dwordx4 v230, s[56:57]
	v_mfma_f32_16x16x32_bf16 v[22:25], v[166:169], v[134:137], v[22:25]
	global_load_lds_dwordx4 v231, s[56:57] offset:1024
	v_mfma_f32_16x16x32_bf16 v[26:29], v[170:173], v[134:137], v[26:29]
	v_mfma_f32_16x16x32_bf16 v[30:33], v[174:177], v[134:137], v[30:33]
	v_mfma_f32_16x16x32_bf16 v[34:37], v[162:165], v[138:141], v[34:37]
	ds_read_b128 v[210:213], v241 offset:0
	v_mfma_f32_16x16x32_bf16 v[38:41], v[166:169], v[138:141], v[38:41]
	ds_read_b128 v[214:217], v241 offset:256
	v_mfma_f32_16x16x32_bf16 v[42:45], v[170:173], v[138:141], v[42:45]
	ds_read_b128 v[218:221], v241 offset:2048
	v_mfma_f32_16x16x32_bf16 v[46:49], v[174:177], v[138:141], v[46:49]
	ds_read_b128 v[222:225], v241 offset:2304
	v_mfma_f32_16x16x32_bf16 v[50:53], v[162:165], v[142:145], v[50:53]
	ds_read_b128 v[178:181], v240 offset:0
	v_mfma_f32_16x16x32_bf16 v[54:57], v[166:169], v[142:145], v[54:57]
	ds_read_b128 v[182:185], v240 offset:1024
	v_mfma_f32_16x16x32_bf16 v[58:61], v[170:173], v[142:145], v[58:61]
	ds_read_b128 v[186:189], v240 offset:2048
	v_mfma_f32_16x16x32_bf16 v[62:65], v[174:177], v[142:145], v[62:65]
	ds_read_b128 v[190:193], v240 offset:3072
	s_cmp_lg_u32 s24, 0
	s_cbranch_scc1 .Lpj_hs7
	v_mfma_f32_16x16x32_bf16 v[66:69], v[162:165], v[146:149], v[66:69]
	ds_read_b128 v[194:197], v240 offset:4096
	v_mfma_f32_16x16x32_bf16 v[70:73], v[166:169], v[146:149], v[70:73]
	ds_read_b128 v[198:201], v240 offset:5120
	v_mfma_f32_16x16x32_bf16 v[74:77], v[170:173], v[146:149], v[74:77]
	ds_read_b128 v[202:205], v240 offset:6144
	v_mfma_f32_16x16x32_bf16 v[78:81], v[174:177], v[146:149], v[78:81]
	ds_read_b128 v[206:209], v240 offset:7168
	s_setprio 1
	v_mfma_f32_16x16x32_bf16 v[82:85], v[162:165], v[150:153], v[82:85]
	v_mfma_f32_16x16x32_bf16 v[86:89], v[166:169], v[150:153], v[86:89]
	v_mfma_f32_16x16x32_bf16 v[90:93], v[170:173], v[150:153], v[90:93]
	v_mfma_f32_16x16x32_bf16 v[94:97], v[174:177], v[150:153], v[94:97]
	v_mfma_f32_16x16x32_bf16 v[98:101], v[162:165], v[154:157], v[98:101]
	v_mfma_f32_16x16x32_bf16 v[102:105], v[166:169], v[154:157], v[102:105]
	v_mfma_f32_16x16x32_bf16 v[106:109], v[170:173], v[154:157], v[106:109]
	v_mfma_f32_16x16x32_bf16 v[110:113], v[174:177], v[154:157], v[110:113]
	v_mfma_f32_16x16x32_bf16 v[114:117], v[162:165], v[158:161], v[114:117]
	v_mfma_f32_16x16x32_bf16 v[118:121], v[166:169], v[158:161], v[118:121]
	v_mfma_f32_16x16x32_bf16 v[122:125], v[170:173], v[158:161], v[122:125]
	v_mfma_f32_16x16x32_bf16 v[126:129], v[174:177], v[158:161], v[126:129]
.Lpj_hs7:
	s_setprio 0
	s_add_i32 s60, s60, 0x6000
	s_cmp_eq_u32 s60, 0x12000
	s_cselect_b32 s60, 0, s60
	s_add_u32 s54, s54, s72
	s_addc_u32 s55, s55, 0
	s_add_u32 s56, s56, s73
	s_addc_u32 s57, s57, 0
	s_add_i32 s61, s61, 0x6000
	s_cmp_eq_u32 s61, 0x12000
	s_cselect_b32 s61, 0, s61
	v_mov_b32_e32 v226, v232
	v_mov_b32_e32 v230, v236
	v_mov_b32_e32 v231, v237
	s_mov_b64 s[54:55], s[48:49]
	s_mov_b64 s[56:57], s[50:51]
	s_waitcnt vmcnt(6) lgkmcnt(0)
	s_barrier
	v_add_u32_e32 v240, s61, v238
	v_add_u32_e32 v241, s61, v239
	s_add_i32 m0, s60, s62
	v_mfma_f32_16x16x32_bf16 v[2:5], v[210:213], v[178:181], v[2:5]
	global_load_lds_dwordx4 v226, s[54:55]
	v_mfma_f32_16x16x32_bf16 v[6:9], v[214:217], v[178:181], v[6:9]
	global_load_lds_dwordx4 v226, s[54:55] offset:1024
	v_mfma_f32_16x16x32_bf16 v[10:13], v[218:221], v[178:181], v[10:13]
	global_load_lds_dwordx4 v226, s[54:55] offset:2048
	v_mfma_f32_16x16x32_bf16 v[14:17], v[222:225], v[178:181], v[14:17]
	global_load_lds_dwordx4 v226, s[54:55] offset:3072
	s_add_i32 m0, s60, s63
	v_mfma_f32_16x16x32_bf16 v[18:21], v[210:213], v[182:185], v[18:21]
	global_load_lds_dwordx4 v230, s[56:57]
	v_mfma_f32_16x16x32_bf16 v[22:25], v[214:217], v[182:185], v[22:25]
	global_load_lds_dwordx4 v231, s[56:57] offset:1024
	v_mfma_f32_16x16x32_bf16 v[26:29], v[218:221], v[182:185], v[26:29]
	v_mfma_f32_16x16x32_bf16 v[30:33], v[222:225], v[182:185], v[30:33]
	v_mfma_f32_16x16x32_bf16 v[34:37], v[210:213], v[186:189], v[34:37]
	ds_read_b128 v[162:165], v241 offset:0
	v_mfma_f32_16x16x32_bf16 v[38:41], v[214:217], v[186:189], v[38:41]
	ds_read_b128 v[166:169], v241 offset:256
	v_mfma_f32_16x16x32_bf16 v[42:45], v[218:221], v[186:189], v[42:45]
	ds_read_b128 v[170:173], v241 offset:2048
	v_mfma_f32_16x16x32_bf16 v[46:49], v[222:225], v[186:189], v[46:49]
	ds_read_b128 v[174:177], v241 offset:2304
	v_mfma_f32_16x16x32_bf16 v[50:53], v[210:213], v[190:193], v[50:53]
	ds_read_b128 v[130:133], v240 offset:0
	v_mfma_f32_16x16x32_bf16 v[54:57], v[214:217], v[190:193], v[54:57]
	ds_read_b128 v[134:137], v240 offset:1024
	v_mfma_f32_16x16x32_bf16 v[58:61], v[218:221], v[190:193], v[58:61]
	ds_read_b128 v[138:141], v240 offset:2048
	v_mfma_f32_16x16x32_bf16 v[62:65], v[222:225], v[190:193], v[62:65]
	ds_read_b128 v[142:145], v240 offset:3072
	s_cmp_lg_u32 s24, 0
	s_cbranch_scc1 .Lpj_hs8
	v_mfma_f32_16x16x32_bf16 v[66:69], v[210:213], v[194:197], v[66:69]
	ds_read_b128 v[146:149], v240 offset:4096
	v_mfma_f32_16x16x32_bf16 v[70:73], v[214:217], v[194:197], v[70:73]
	ds_read_b128 v[150:153], v240 offset:5120
	v_mfma_f32_16x16x32_bf16 v[74:77], v[218:221], v[194:197], v[74:77]
	ds_read_b128 v[154:157], v240 offset:6144
	v_mfma_f32_16x16x32_bf16 v[78:81], v[222:225], v[194:197], v[78:81]
	ds_read_b128 v[158:161], v240 offset:7168
	s_setprio 1
	v_mfma_f32_16x16x32_bf16 v[82:85], v[210:213], v[198:201], v[82:85]
	v_mfma_f32_16x16x32_bf16 v[86:89], v[214:217], v[198:201], v[86:89]
	v_mfma_f32_16x16x32_bf16 v[90:93], v[218:221], v[198:201], v[90:93]
	v_mfma_f32_16x16x32_bf16 v[94:97], v[222:225], v[198:201], v[94:97]
	v_mfma_f32_16x16x32_bf16 v[98:101], v[210:213], v[202:205], v[98:101]
	v_mfma_f32_16x16x32_bf16 v[102:105], v[214:217], v[202:205], v[102:105]
	v_mfma_f32_16x16x32_bf16 v[106:109], v[218:221], v[202:205], v[106:109]
	v_mfma_f32_16x16x32_bf16 v[110:113], v[222:225], v[202:205], v[110:113]
	v_mfma_f32_16x16x32_bf16 v[114:117], v[210:213], v[206:209], v[114:117]
	v_mfma_f32_16x16x32_bf16 v[118:121], v[214:217], v[206:209], v[118:121]
	v_mfma_f32_16x16x32_bf16 v[122:125], v[218:221], v[206:209], v[122:125]
	v_mfma_f32_16x16x32_bf16 v[126:129], v[222:225], v[206:209], v[126:129]
.Lpj_hs8:
	s_setprio 0
	s_add_i32 s60, s60, 0x6000
	s_cmp_eq_u32 s60, 0x12000
	s_cselect_b32 s60, 0, s60
	s_add_u32 s54, s54, s72
	s_addc_u32 s55, s55, 0
	s_add_u32 s56, s56, s73
	s_addc_u32 s57, s57, 0
	s_add_i32 s61, s61, 0x6000
	s_cmp_eq_u32 s61, 0x12000
	s_cselect_b32 s61, 0, s61
	s_waitcnt vmcnt(6) lgkmcnt(0)
	s_barrier
	v_add_u32_e32 v240, s61, v238
	v_add_u32_e32 v241, s61, v239
	s_add_i32 m0, s60, s62
	v_mfma_f32_16x16x32_bf16 v[2:5], v[162:165], v[130:133], v[2:5]
	global_load_lds_dwordx4 v226, s[54:55]
	v_mfma_f32_16x16x32_bf16 v[6:9], v[166:169], v[130:133], v[6:9]
	global_load_lds_dwordx4 v226, s[54:55] offset:1024
	v_mfma_f32_16x16x32_bf16 v[10:13], v[170:173], v[130:133], v[10:13]
	global_load_lds_dwordx4 v226, s[54:55] offset:2048
	v_mfma_f32_16x16x32_bf16 v[14:17], v[174:177], v[130:133], v[14:17]
	global_load_lds_dwordx4 v226, s[54:55] offset:3072
	s_add_i32 m0, s60, s63
	v_mfma_f32_16x16x32_bf16 v[18:21], v[162:165], v[134:137], v[18:21]
	global_load_lds_dwordx4 v230, s[56:57]
	v_mfma_f32_16x16x32_bf16 v[22:25], v[166:169], v[134:137], v[22:25]
	global_load_lds_dwordx4 v231, s[56:57] offset:1024
	v_mfma_f32_16x16x32_bf16 v[26:29], v[170:173], v[134:137], v[26:29]
	v_mfma_f32_16x16x32_bf16 v[30:33], v[174:177], v[134:137], v[30:33]
	v_mfma_f32_16x16x32_bf16 v[34:37], v[162:165], v[138:141], v[34:37]
	ds_read_b128 v[210:213], v241 offset:0
	v_mfma_f32_16x16x32_bf16 v[38:41], v[166:169], v[138:141], v[38:41]
	ds_read_b128 v[214:217], v241 offset:256
	v_mfma_f32_16x16x32_bf16 v[42:45], v[170:173], v[138:141], v[42:45]
	ds_read_b128 v[218:221], v241 offset:2048
	v_mfma_f32_16x16x32_bf16 v[46:49], v[174:177], v[138:141], v[46:49]
	ds_read_b128 v[222:225], v241 offset:2304
	v_mfma_f32_16x16x32_bf16 v[50:53], v[162:165], v[142:145], v[50:53]
	ds_read_b128 v[178:181], v240 offset:0
	v_mfma_f32_16x16x32_bf16 v[54:57], v[166:169], v[142:145], v[54:57]
	ds_read_b128 v[182:185], v240 offset:1024
	v_mfma_f32_16x16x32_bf16 v[58:61], v[170:173], v[142:145], v[58:61]
	ds_read_b128 v[186:189], v240 offset:2048
	v_mfma_f32_16x16x32_bf16 v[62:65], v[174:177], v[142:145], v[62:65]
	ds_read_b128 v[190:193], v240 offset:3072
	s_cmp_lg_u32 s24, 0
	s_cbranch_scc1 .Lpj_hs9
	v_mfma_f32_16x16x32_bf16 v[66:69], v[162:165], v[146:149], v[66:69]
	ds_read_b128 v[194:197], v240 offset:4096
	v_mfma_f32_16x16x32_bf16 v[70:73], v[166:169], v[146:149], v[70:73]
	ds_read_b128 v[198:201], v240 offset:5120
	v_mfma_f32_16x16x32_bf16 v[74:77], v[170:173], v[146:149], v[74:77]
	ds_read_b128 v[202:205], v240 offset:6144
	v_mfma_f32_16x16x32_bf16 v[78:81], v[174:177], v[146:149], v[78:81]
	ds_read_b128 v[206:209], v240 offset:7168
	s_setprio 1
	v_mfma_f32_16x16x32_bf16 v[82:85], v[162:165], v[150:153], v[82:85]
	v_mfma_f32_16x16x32_bf16 v[86:89], v[166:169], v[150:153], v[86:89]
	v_mfma_f32_16x16x32_bf16 v[90:93], v[170:173], v[150:153], v[90:93]
	v_mfma_f32_16x16x32_bf16 v[94:97], v[174:177], v[150:153], v[94:97]
	v_mfma_f32_16x16x32_bf16 v[98:101], v[162:165], v[154:157], v[98:101]
	v_mfma_f32_16x16x32_bf16 v[102:105], v[166:169], v[154:157], v[102:105]
	v_mfma_f32_16x16x32_bf16 v[106:109], v[170:173], v[154:157], v[106:109]
	v_mfma_f32_16x16x32_bf16 v[110:113], v[174:177], v[154:157], v[110:113]
	v_mfma_f32_16x16x32_bf16 v[114:117], v[162:165], v[158:161], v[114:117]
	v_mfma_f32_16x16x32_bf16 v[118:121], v[166:169], v[158:161], v[118:121]
	v_mfma_f32_16x16x32_bf16 v[122:125], v[170:173], v[158:161], v[122:125]
	v_mfma_f32_16x16x32_bf16 v[126:129], v[174:177], v[158:161], v[126:129]

.Lpj_ret_n:
	s_mov_b32 s34, s38
	s_mov_b32 s35, s30
	s_mov_b32 s36, s31
	s_mov_b32 s24, s28
	s_branch .Lpj_tile

.Lpj_hs11:
	s_setprio 0
	s_add_i32 s60, s60, 0x6000
	s_cmp_eq_u32 s60, 0x12000
	s_cselect_b32 s60, 0, s60
	s_add_u32 s54, s54, s72
	s_addc_u32 s55, s55, 0
	s_add_u32 s56, s56, s73
	s_addc_u32 s57, s57, 0
	s_add_i32 s61, s61, 0x6000
	s_cmp_eq_u32 s61, 0x12000
	s_cselect_b32 s61, 0, s61
	s_waitcnt vmcnt(6) lgkmcnt(0)
	s_barrier
	v_add_u32_e32 v240, s61, v238
	v_add_u32_e32 v241, s61, v239
	v_mfma_f32_16x16x32_bf16 v[2:5], v[210:213], v[178:181], v[2:5]
	v_mfma_f32_16x16x32_bf16 v[6:9], v[214:217], v[178:181], v[6:9]
	v_mfma_f32_16x16x32_bf16 v[10:13], v[218:221], v[178:181], v[10:13]
	v_mfma_f32_16x16x32_bf16 v[14:17], v[222:225], v[178:181], v[14:17]
	v_mfma_f32_16x16x32_bf16 v[18:21], v[210:213], v[182:185], v[18:21]
	v_mfma_f32_16x16x32_bf16 v[22:25], v[214:217], v[182:185], v[22:25]
	v_mfma_f32_16x16x32_bf16 v[26:29], v[218:221], v[182:185], v[26:29]
	v_mfma_f32_16x16x32_bf16 v[30:33], v[222:225], v[182:185], v[30:33]
	v_mfma_f32_16x16x32_bf16 v[34:37], v[210:213], v[186:189], v[34:37]
	ds_read_b128 v[162:165], v241 offset:0
	v_mfma_f32_16x16x32_bf16 v[38:41], v[214:217], v[186:189], v[38:41]
	ds_read_b128 v[166:169], v241 offset:256
	v_mfma_f32_16x16x32_bf16 v[42:45], v[218:221], v[186:189], v[42:45]
	ds_read_b128 v[170:173], v241 offset:2048
	v_mfma_f32_16x16x32_bf16 v[46:49], v[222:225], v[186:189], v[46:49]
	ds_read_b128 v[174:177], v241 offset:2304
	v_mfma_f32_16x16x32_bf16 v[50:53], v[210:213], v[190:193], v[50:53]
	ds_read_b128 v[130:133], v240 offset:0
	v_mfma_f32_16x16x32_bf16 v[54:57], v[214:217], v[190:193], v[54:57]
	ds_read_b128 v[134:137], v240 offset:1024
	v_mfma_f32_16x16x32_bf16 v[58:61], v[218:221], v[190:193], v[58:61]
	ds_read_b128 v[138:141], v240 offset:2048
	v_mfma_f32_16x16x32_bf16 v[62:65], v[222:225], v[190:193], v[62:65]
	ds_read_b128 v[142:145], v240 offset:3072
	s_cmp_lg_u32 s24, 0
	s_cbranch_scc1 .Lpj_hs12
	v_mfma_f32_16x16x32_bf16 v[66:69], v[210:213], v[194:197], v[66:69]
	ds_read_b128 v[146:149], v240 offset:4096
	v_mfma_f32_16x16x32_bf16 v[70:73], v[214:217], v[194:197], v[70:73]
	ds_read_b128 v[150:153], v240 offset:5120
	v_mfma_f32_16x16x32_bf16 v[74:77], v[218:221], v[194:197], v[74:77]
	ds_read_b128 v[154:157], v240 offset:6144
	v_mfma_f32_16x16x32_bf16 v[78:81], v[222:225], v[194:197], v[78:81]
	ds_read_b128 v[158:161], v240 offset:7168
	s_setprio 1
	v_mfma_f32_16x16x32_bf16 v[82:85], v[210:213], v[198:201], v[82:85]
	v_mfma_f32_16x16x32_bf16 v[86:89], v[214:217], v[198:201], v[86:89]
	v_mfma_f32_16x16x32_bf16 v[90:93], v[218:221], v[198:201], v[90:93]
	v_mfma_f32_16x16x32_bf16 v[94:97], v[222:225], v[198:201], v[94:97]
	v_mfma_f32_16x16x32_bf16 v[98:101], v[210:213], v[202:205], v[98:101]
	v_mfma_f32_16x16x32_bf16 v[102:105], v[214:217], v[202:205], v[102:105]
	v_mfma_f32_16x16x32_bf16 v[106:109], v[218:221], v[202:205], v[106:109]
	v_mfma_f32_16x16x32_bf16 v[110:113], v[222:225], v[202:205], v[110:113]
	v_mfma_f32_16x16x32_bf16 v[114:117], v[210:213], v[206:209], v[114:117]
	v_mfma_f32_16x16x32_bf16 v[118:121], v[214:217], v[206:209], v[118:121]
	v_mfma_f32_16x16x32_bf16 v[122:125], v[218:221], v[206:209], v[122:125]
	v_mfma_f32_16x16x32_bf16 v[126:129], v[222:225], v[206:209], v[126:129]
.Lpj_hs12:
	s_setprio 0
	s_add_i32 s61, s61, 0x6000
	s_cmp_eq_u32 s61, 0x12000
	s_cselect_b32 s61, 0, s61
	s_waitcnt vmcnt(0) lgkmcnt(0)
	s_barrier
	v_add_u32_e32 v240, s61, v238
	v_add_u32_e32 v241, s61, v239
	v_mfma_f32_16x16x32_bf16 v[2:5], v[162:165], v[130:133], v[2:5]
	v_mfma_f32_16x16x32_bf16 v[6:9], v[166:169], v[130:133], v[6:9]
	v_mfma_f32_16x16x32_bf16 v[10:13], v[170:173], v[130:133], v[10:13]
	v_mfma_f32_16x16x32_bf16 v[14:17], v[174:177], v[130:133], v[14:17]
	v_mfma_f32_16x16x32_bf16 v[18:21], v[162:165], v[134:137], v[18:21]
	v_mfma_f32_16x16x32_bf16 v[22:25], v[166:169], v[134:137], v[22:25]
	v_mfma_f32_16x16x32_bf16 v[26:29], v[170:173], v[134:137], v[26:29]
	v_mfma_f32_16x16x32_bf16 v[30:33], v[174:177], v[134:137], v[30:33]
	v_mfma_f32_16x16x32_bf16 v[34:37], v[162:165], v[138:141], v[34:37]
	ds_read_b128 v[210:213], v241 offset:0
	v_mfma_f32_16x16x32_bf16 v[38:41], v[166:169], v[138:141], v[38:41]
	ds_read_b128 v[214:217], v241 offset:256
	v_mfma_f32_16x16x32_bf16 v[42:45], v[170:173], v[138:141], v[42:45]
	ds_read_b128 v[218:221], v241 offset:2048
	v_mfma_f32_16x16x32_bf16 v[46:49], v[174:177], v[138:141], v[46:49]
	ds_read_b128 v[222:225], v241 offset:2304
	v_mfma_f32_16x16x32_bf16 v[50:53], v[162:165], v[142:145], v[50:53]
	ds_read_b128 v[178:181], v240 offset:0
	v_mfma_f32_16x16x32_bf16 v[54:57], v[166:169], v[142:145], v[54:57]
	ds_read_b128 v[182:185], v240 offset:1024
	v_mfma_f32_16x16x32_bf16 v[58:61], v[170:173], v[142:145], v[58:61]
	ds_read_b128 v[186:189], v240 offset:2048
	v_mfma_f32_16x16x32_bf16 v[62:65], v[174:177], v[142:145], v[62:65]
	ds_read_b128 v[190:193], v240 offset:3072
	s_cmp_lg_u32 s24, 0
	s_cbranch_scc1 .Lpj_hs13
	v_mfma_f32_16x16x32_bf16 v[66:69], v[162:165], v[146:149], v[66:69]
	ds_read_b128 v[194:197], v240 offset:4096
	v_mfma_f32_16x16x32_bf16 v[70:73], v[166:169], v[146:149], v[70:73]
	ds_read_b128 v[198:201], v240 offset:5120
	v_mfma_f32_16x16x32_bf16 v[74:77], v[170:173], v[146:149], v[74:77]
	ds_read_b128 v[202:205], v240 offset:6144
	v_mfma_f32_16x16x32_bf16 v[78:81], v[174:177], v[146:149], v[78:81]
	ds_read_b128 v[206:209], v240 offset:7168
	s_setprio 1
	v_mfma_f32_16x16x32_bf16 v[82:85], v[162:165], v[150:153], v[82:85]
	v_mfma_f32_16x16x32_bf16 v[86:89], v[166:169], v[150:153], v[86:89]
	v_mfma_f32_16x16x32_bf16 v[90:93], v[170:173], v[150:153], v[90:93]
	v_mfma_f32_16x16x32_bf16 v[94:97], v[174:177], v[150:153], v[94:97]
	v_mfma_f32_16x16x32_bf16 v[98:101], v[162:165], v[154:157], v[98:101]
	v_mfma_f32_16x16x32_bf16 v[102:105], v[166:169], v[154:157], v[102:105]
	v_mfma_f32_16x16x32_bf16 v[106:109], v[170:173], v[154:157], v[106:109]
	v_mfma_f32_16x16x32_bf16 v[110:113], v[174:177], v[154:157], v[110:113]
	v_mfma_f32_16x16x32_bf16 v[114:117], v[162:165], v[158:161], v[114:117]
	v_mfma_f32_16x16x32_bf16 v[118:121], v[166:169], v[158:161], v[118:121]
	v_mfma_f32_16x16x32_bf16 v[122:125], v[170:173], v[158:161], v[122:125]
	v_mfma_f32_16x16x32_bf16 v[126:129], v[174:177], v[158:161], v[126:129]
.Lpj_hs13:
	s_setprio 0
	s_add_i32 s61, s61, 0x6000
	s_cmp_eq_u32 s61, 0x12000
	s_cselect_b32 s61, 0, s61
	s_waitcnt lgkmcnt(0)
	s_barrier
	v_mfma_f32_16x16x32_bf16 v[2:5], v[210:213], v[178:181], v[2:5]
	v_mfma_f32_16x16x32_bf16 v[6:9], v[214:217], v[178:181], v[6:9]
	v_mfma_f32_16x16x32_bf16 v[10:13], v[218:221], v[178:181], v[10:13]
	v_mfma_f32_16x16x32_bf16 v[14:17], v[222:225], v[178:181], v[14:17]
	v_mfma_f32_16x16x32_bf16 v[18:21], v[210:213], v[182:185], v[18:21]
	v_mfma_f32_16x16x32_bf16 v[22:25], v[214:217], v[182:185], v[22:25]
	v_mfma_f32_16x16x32_bf16 v[26:29], v[218:221], v[182:185], v[26:29]
	v_mfma_f32_16x16x32_bf16 v[30:33], v[222:225], v[182:185], v[30:33]
	v_mfma_f32_16x16x32_bf16 v[34:37], v[210:213], v[186:189], v[34:37]
	v_mfma_f32_16x16x32_bf16 v[38:41], v[214:217], v[186:189], v[38:41]
	v_mfma_f32_16x16x32_bf16 v[42:45], v[218:221], v[186:189], v[42:45]
	v_mfma_f32_16x16x32_bf16 v[46:49], v[222:225], v[186:189], v[46:49]
	v_mfma_f32_16x16x32_bf16 v[50:53], v[210:213], v[190:193], v[50:53]
	v_mfma_f32_16x16x32_bf16 v[54:57], v[214:217], v[190:193], v[54:57]
	v_mfma_f32_16x16x32_bf16 v[58:61], v[218:221], v[190:193], v[58:61]
	v_mfma_f32_16x16x32_bf16 v[62:65], v[222:225], v[190:193], v[62:65]
	s_cmp_lg_u32 s24, 0
	s_cbranch_scc1 .Lpj_hs14
	v_mfma_f32_16x16x32_bf16 v[66:69], v[210:213], v[194:197], v[66:69]
	v_mfma_f32_16x16x32_bf16 v[70:73], v[214:217], v[194:197], v[70:73]
	v_mfma_f32_16x16x32_bf16 v[74:77], v[218:221], v[194:197], v[74:77]
	v_mfma_f32_16x16x32_bf16 v[78:81], v[222:225], v[194:197], v[78:81]
	s_setprio 1
	v_mfma_f32_16x16x32_bf16 v[82:85], v[210:213], v[198:201], v[82:85]
	v_mfma_f32_16x16x32_bf16 v[86:89], v[214:217], v[198:201], v[86:89]
	v_mfma_f32_16x16x32_bf16 v[90:93], v[218:221], v[198:201], v[90:93]
	v_mfma_f32_16x16x32_bf16 v[94:97], v[222:225], v[198:201], v[94:97]
	v_mfma_f32_16x16x32_bf16 v[98:101], v[210:213], v[202:205], v[98:101]
	v_mfma_f32_16x16x32_bf16 v[102:105], v[214:217], v[202:205], v[102:105]
	v_mfma_f32_16x16x32_bf16 v[106:109], v[218:221], v[202:205], v[106:109]
	v_mfma_f32_16x16x32_bf16 v[110:113], v[222:225], v[202:205], v[110:113]
	v_mfma_f32_16x16x32_bf16 v[114:117], v[210:213], v[206:209], v[114:117]
	v_mfma_f32_16x16x32_bf16 v[118:121], v[214:217], v[206:209], v[118:121]
	v_mfma_f32_16x16x32_bf16 v[122:125], v[218:221], v[206:209], v[122:125]
	v_mfma_f32_16x16x32_bf16 v[126:129], v[222:225], v[206:209], v[126:129]
.Lpj_hs14:
	s_setprio 0

.Lpj_row:
	s_lshl_b32 s26, s43, 6
	s_add_i32 s66, s66, s26
	v_mul_lo_u32 v179, v227, s39
	v_add_u32_e32 v179, v179, v228
	s_mul_i32 s26, s35, s39
	s_lshl_b32 s27, s66, 1
	s_add_i32 s26, s26, s27
	s_lshl_b32 s27, s39, 4
	s_waitcnt vmcnt(0) lgkmcnt(0)
	s_add_u32 s6, s18, s26
	s_addc_u32 s7, s19, 0
	v_mul_f32_e32 v2, s21, v2
	v_mul_f32_e32 v3, s21, v3
	v_mul_f32_e32 v4, s21, v4
	v_mul_f32_e32 v5, s21, v5
	v_mul_f32_e32 v6, s21, v6
	v_mul_f32_e32 v7, s21, v7
	v_mul_f32_e32 v8, s21, v8
	v_mul_f32_e32 v9, s21, v9
	v_cvt_pk_bf16_f32 v2, v2, v3
	v_cvt_pk_bf16_f32 v3, v4, v5
	v_cvt_pk_bf16_f32 v4, v6, v7
	v_cvt_pk_bf16_f32 v5, v8, v9
	global_store_dwordx4 v179, v[2:5], s[6:7]
	v_mul_f32_e32 v10, s21, v10
	v_mul_f32_e32 v11, s21, v11
	v_mul_f32_e32 v12, s21, v12
	v_mul_f32_e32 v13, s21, v13
	v_mul_f32_e32 v14, s21, v14
	v_mul_f32_e32 v15, s21, v15
	v_mul_f32_e32 v16, s21, v16
	v_mul_f32_e32 v17, s21, v17
	v_cvt_pk_bf16_f32 v10, v10, v11
	v_cvt_pk_bf16_f32 v11, v12, v13
	v_cvt_pk_bf16_f32 v12, v14, v15
	v_cvt_pk_bf16_f32 v13, v16, v17
	global_store_dwordx4 v179, v[10:13], s[6:7] offset:64
	s_add_u32 s6, s6, s27
	s_addc_u32 s7, s7, 0
	v_mul_f32_e32 v18, s21, v18
	v_mul_f32_e32 v19, s21, v19
	v_mul_f32_e32 v20, s21, v20
	v_mul_f32_e32 v21, s21, v21
	v_mul_f32_e32 v22, s21, v22
	v_mul_f32_e32 v23, s21, v23
	v_mul_f32_e32 v24, s21, v24
	v_mul_f32_e32 v25, s21, v25
	v_cvt_pk_bf16_f32 v18, v18, v19
	v_cvt_pk_bf16_f32 v19, v20, v21
	v_cvt_pk_bf16_f32 v20, v22, v23
	v_cvt_pk_bf16_f32 v21, v24, v25
	global_store_dwordx4 v179, v[18:21], s[6:7]
	v_mul_f32_e32 v26, s21, v26
	v_mul_f32_e32 v27, s21, v27
	v_mul_f32_e32 v28, s21, v28
	v_mul_f32_e32 v29, s21, v29
	v_mul_f32_e32 v30, s21, v30
	v_mul_f32_e32 v31, s21, v31
	v_mul_f32_e32 v32, s21, v32
	v_mul_f32_e32 v33, s21, v33
	v_cvt_pk_bf16_f32 v26, v26, v27
	v_cvt_pk_bf16_f32 v27, v28, v29
	v_cvt_pk_bf16_f32 v28, v30, v31
	v_cvt_pk_bf16_f32 v29, v32, v33
	global_store_dwordx4 v179, v[26:29], s[6:7] offset:64
	s_add_u32 s6, s6, s27
	s_addc_u32 s7, s7, 0
	v_mul_f32_e32 v34, s21, v34
	v_mul_f32_e32 v35, s21, v35
	v_mul_f32_e32 v36, s21, v36
	v_mul_f32_e32 v37, s21, v37
	v_mul_f32_e32 v38, s21, v38
	v_mul_f32_e32 v39, s21, v39
	v_mul_f32_e32 v40, s21, v40
	v_mul_f32_e32 v41, s21, v41
	v_cvt_pk_bf16_f32 v34, v34, v35
	v_cvt_pk_bf16_f32 v35, v36, v37
	v_cvt_pk_bf16_f32 v36, v38, v39
	v_cvt_pk_bf16_f32 v37, v40, v41
	global_store_dwordx4 v179, v[34:37], s[6:7]
	v_mul_f32_e32 v42, s21, v42
	v_mul_f32_e32 v43, s21, v43
	v_mul_f32_e32 v44, s21, v44
	v_mul_f32_e32 v45, s21, v45
	v_mul_f32_e32 v46, s21, v46
	v_mul_f32_e32 v47, s21, v47
	v_mul_f32_e32 v48, s21, v48
	v_mul_f32_e32 v49, s21, v49
	v_cvt_pk_bf16_f32 v42, v42, v43
	v_cvt_pk_bf16_f32 v43, v44, v45
	v_cvt_pk_bf16_f32 v44, v46, v47
	v_cvt_pk_bf16_f32 v45, v48, v49
	global_store_dwordx4 v179, v[42:45], s[6:7] offset:64
	s_add_u32 s6, s6, s27
	s_addc_u32 s7, s7, 0
	v_mul_f32_e32 v50, s21, v50
	v_mul_f32_e32 v51, s21, v51
	v_mul_f32_e32 v52, s21, v52
	v_mul_f32_e32 v53, s21, v53
	v_mul_f32_e32 v54, s21, v54
	v_mul_f32_e32 v55, s21, v55
	v_mul_f32_e32 v56, s21, v56
	v_mul_f32_e32 v57, s21, v57
	v_cvt_pk_bf16_f32 v50, v50, v51
	v_cvt_pk_bf16_f32 v51, v52, v53
	v_cvt_pk_bf16_f32 v52, v54, v55
	v_cvt_pk_bf16_f32 v53, v56, v57
	global_store_dwordx4 v179, v[50:53], s[6:7]
	v_mul_f32_e32 v58, s21, v58
	v_mul_f32_e32 v59, s21, v59
	v_mul_f32_e32 v60, s21, v60
	v_mul_f32_e32 v61, s21, v61
	v_mul_f32_e32 v62, s21, v62
	v_mul_f32_e32 v63, s21, v63
	v_mul_f32_e32 v64, s21, v64
	v_mul_f32_e32 v65, s21, v65
	v_cvt_pk_bf16_f32 v58, v58, v59
	v_cvt_pk_bf16_f32 v59, v60, v61
	v_cvt_pk_bf16_f32 v60, v62, v63
	v_cvt_pk_bf16_f32 v61, v64, v65
	global_store_dwordx4 v179, v[58:61], s[6:7] offset:64
	s_add_u32 s6, s6, s27
	s_addc_u32 s7, s7, 0
	s_cmp_lg_u32 s24, 0
	s_cbranch_scc1 .Lpj_epi_end
	v_mul_f32_e32 v66, s21, v66
	v_mul_f32_e32 v67, s21, v67
	v_mul_f32_e32 v68, s21, v68
	v_mul_f32_e32 v69, s21, v69
	v_mul_f32_e32 v70, s21, v70
	v_mul_f32_e32 v71, s21, v71
	v_mul_f32_e32 v72, s21, v72
	v_mul_f32_e32 v73, s21, v73
	v_cvt_pk_bf16_f32 v66, v66, v67
	v_cvt_pk_bf16_f32 v67, v68, v69
	v_cvt_pk_bf16_f32 v68, v70, v71
	v_cvt_pk_bf16_f32 v69, v72, v73
	global_store_dwordx4 v179, v[66:69], s[6:7]
	v_mul_f32_e32 v74, s21, v74
	v_mul_f32_e32 v75, s21, v75
	v_mul_f32_e32 v76, s21, v76
	v_mul_f32_e32 v77, s21, v77
	v_mul_f32_e32 v78, s21, v78
	v_mul_f32_e32 v79, s21, v79
	v_mul_f32_e32 v80, s21, v80
	v_mul_f32_e32 v81, s21, v81
	v_cvt_pk_bf16_f32 v74, v74, v75
	v_cvt_pk_bf16_f32 v75, v76, v77
	v_cvt_pk_bf16_f32 v76, v78, v79
	v_cvt_pk_bf16_f32 v77, v80, v81
	global_store_dwordx4 v179, v[74:77], s[6:7] offset:64
	s_add_u32 s6, s6, s27
	s_addc_u32 s7, s7, 0
	v_mul_f32_e32 v82, s21, v82
	v_mul_f32_e32 v83, s21, v83
	v_mul_f32_e32 v84, s21, v84
	v_mul_f32_e32 v85, s21, v85
	v_mul_f32_e32 v86, s21, v86
	v_mul_f32_e32 v87, s21, v87
	v_mul_f32_e32 v88, s21, v88
	v_mul_f32_e32 v89, s21, v89
	v_cvt_pk_bf16_f32 v82, v82, v83
	v_cvt_pk_bf16_f32 v83, v84, v85
	v_cvt_pk_bf16_f32 v84, v86, v87
	v_cvt_pk_bf16_f32 v85, v88, v89
	global_store_dwordx4 v179, v[82:85], s[6:7]
	v_mul_f32_e32 v90, s21, v90
	v_mul_f32_e32 v91, s21, v91
	v_mul_f32_e32 v92, s21, v92
	v_mul_f32_e32 v93, s21, v93
	v_mul_f32_e32 v94, s21, v94
	v_mul_f32_e32 v95, s21, v95
	v_mul_f32_e32 v96, s21, v96
	v_mul_f32_e32 v97, s21, v97
	v_cvt_pk_bf16_f32 v90, v90, v91
	v_cvt_pk_bf16_f32 v91, v92, v93
	v_cvt_pk_bf16_f32 v92, v94, v95
	v_cvt_pk_bf16_f32 v93, v96, v97
	global_store_dwordx4 v179, v[90:93], s[6:7] offset:64
	s_add_u32 s6, s6, s27
	s_addc_u32 s7, s7, 0
	v_mul_f32_e32 v98, s21, v98
	v_mul_f32_e32 v99, s21, v99
	v_mul_f32_e32 v100, s21, v100
	v_mul_f32_e32 v101, s21, v101
	v_mul_f32_e32 v102, s21, v102
	v_mul_f32_e32 v103, s21, v103
	v_mul_f32_e32 v104, s21, v104
	v_mul_f32_e32 v105, s21, v105
	v_cvt_pk_bf16_f32 v98, v98, v99
	v_cvt_pk_bf16_f32 v99, v100, v101
	v_cvt_pk_bf16_f32 v100, v102, v103
	v_cvt_pk_bf16_f32 v101, v104, v105
	global_store_dwordx4 v179, v[98:101], s[6:7]
	v_mul_f32_e32 v106, s21, v106
	v_mul_f32_e32 v107, s21, v107
	v_mul_f32_e32 v108, s21, v108
	v_mul_f32_e32 v109, s21, v109
	v_mul_f32_e32 v110, s21, v110
	v_mul_f32_e32 v111, s21, v111
	v_mul_f32_e32 v112, s21, v112
	v_mul_f32_e32 v113, s21, v113
	v_cvt_pk_bf16_f32 v106, v106, v107
	v_cvt_pk_bf16_f32 v107, v108, v109
	v_cvt_pk_bf16_f32 v108, v110, v111
	v_cvt_pk_bf16_f32 v109, v112, v113
	global_store_dwordx4 v179, v[106:109], s[6:7] offset:64
	s_add_u32 s6, s6, s27
	s_addc_u32 s7, s7, 0
	v_mul_f32_e32 v114, s21, v114
	v_mul_f32_e32 v115, s21, v115
	v_mul_f32_e32 v116, s21, v116
	v_mul_f32_e32 v117, s21, v117
	v_mul_f32_e32 v118, s21, v118
	v_mul_f32_e32 v119, s21, v119
	v_mul_f32_e32 v120, s21, v120
	v_mul_f32_e32 v121, s21, v121
	v_cvt_pk_bf16_f32 v114, v114, v115
	v_cvt_pk_bf16_f32 v115, v116, v117
	v_cvt_pk_bf16_f32 v116, v118, v119
	v_cvt_pk_bf16_f32 v117, v120, v121
	global_store_dwordx4 v179, v[114:117], s[6:7]
	v_mul_f32_e32 v122, s21, v122
	v_mul_f32_e32 v123, s21, v123
	v_mul_f32_e32 v124, s21, v124
	v_mul_f32_e32 v125, s21, v125
	v_mul_f32_e32 v126, s21, v126
	v_mul_f32_e32 v127, s21, v127
	v_mul_f32_e32 v128, s21, v128
	v_mul_f32_e32 v129, s21, v129
	v_cvt_pk_bf16_f32 v122, v122, v123
	v_cvt_pk_bf16_f32 v123, v124, v125
	v_cvt_pk_bf16_f32 v124, v126, v127
	v_cvt_pk_bf16_f32 v125, v128, v129
	global_store_dwordx4 v179, v[122:125], s[6:7] offset:64
	s_branch .Lpj_epi_end

.Lpj_glr:
	s_load_dwordx2 s[18:19], s[0:1], 0x100
	s_lshl_b32 s26, s35, 6
	v_lshlrev_b32_e32 v179, 1, v228
	v_lshl_add_u32 v179, v227, 6, v179
	s_waitcnt vmcnt(0) lgkmcnt(0)
	s_cmp_eq_u32 s43, 0
	s_cbranch_scc0 .Lpj_epi_end
	s_add_u32 s6, s18, s26
	s_addc_u32 s7, s19, 0
	s_mov_b32 exec_lo, -1
	s_mov_b32 exec_hi, 0
	global_store_dwordx4 v179, v[2:5], s[6:7]
	global_store_dwordx4 v179, v[6:9], s[6:7] offset:16
	s_add_u32 s6, s6, 0x400
	s_addc_u32 s7, s7, 0
	global_store_dwordx4 v179, v[18:21], s[6:7]
	global_store_dwordx4 v179, v[22:25], s[6:7] offset:16
	s_add_u32 s6, s6, 0x400
	s_addc_u32 s7, s7, 0
	global_store_dwordx4 v179, v[34:37], s[6:7]
	global_store_dwordx4 v179, v[38:41], s[6:7] offset:16
	s_add_u32 s6, s6, 0x400
	s_addc_u32 s7, s7, 0
	global_store_dwordx4 v179, v[50:53], s[6:7]
	global_store_dwordx4 v179, v[54:57], s[6:7] offset:16
	s_add_u32 s6, s6, 0x400
	s_addc_u32 s7, s7, 0
	s_cmp_lg_u32 s24, 0
	s_cbranch_scc1 .Lpj_glr_x
	global_store_dwordx4 v179, v[66:69], s[6:7]
	global_store_dwordx4 v179, v[70:73], s[6:7] offset:16
	s_add_u32 s6, s6, 0x400
	s_addc_u32 s7, s7, 0
	global_store_dwordx4 v179, v[82:85], s[6:7]
	global_store_dwordx4 v179, v[86:89], s[6:7] offset:16
	s_add_u32 s6, s6, 0x400
	s_addc_u32 s7, s7, 0
	global_store_dwordx4 v179, v[98:101], s[6:7]
	global_store_dwordx4 v179, v[102:105], s[6:7] offset:16
	s_add_u32 s6, s6, 0x400
	s_addc_u32 s7, s7, 0
	global_store_dwordx4 v179, v[114:117], s[6:7]
	global_store_dwordx4 v179, v[118:121], s[6:7] offset:16
.Lpj_glr_x:
	s_mov_b64 exec, -1
